# producer ds_write_b128 spaced apart with s_nop (avoid LDS write bursts from 4 lock-stepped producer waves)
# speedup vs baseline: 1.0142x; 1.0142x over previous
; #define LAS __attribute__((address_space(3)))
; __device__ __forceinline__ float f16_to_f(unsigned short h) { return (float)__builtin_bit_cast(_Float16, h); }
; __device__ __forceinline__ float scan_prepare(const ScanRegs& R, const u32x2 qr_, const u32x2 qk_, const u32x2 qv_, LAS float* slot, int cq, const f32x4 mur, const f32x4 muk, const f32x4 muv, const f32x4 kkc, const f32x4 kac, const f32x4 rkc) {
;     float pr[4], pk[4], pv[4], qr[4], qk[4], qv[4], av[4], om[4];
;     unpack4(R.pr, pr); unpack4(R.pk, pk); unpack4(R.pv, pv); unpack4(qr_, qr); unpack4(qk_, qk); unpack4(qv_, qv); unpack4(R.as, av);
;     om[0] = f16_to_f((unsigned short)(R.wl.x & 0xffffu)); om[1] = f16_to_f((unsigned short)(R.wl.x >> 16)); om[2] = f16_to_f((unsigned short)(R.wl.y & 0xffffu)); om[3] = f16_to_f((unsigned short)(R.wl.y >> 16));
;     float rr[4], vv[4], kn[4], k2[4], dec[4], bu[4];
;     float ssq = 0.f, bon = 0.f, c1 = 0.f, c2 = 0.f;
; #pragma unroll
;     for (int j = 0; j < 4; ++j) {
;         rr[j] = pr[j] + (qr[j] - pr[j]) * mur[j]; const float kk0 = pk[j] + (qk[j] - pk[j]) * muk[j]; vv[j] = pv[j] + (qv[j] - pv[j]) * muv[j];
;         dec[j] = 1.0f - om[j];
;         kn[j] = kk0 * kkc[j]; ssq += kn[j] * kn[j];
;         k2[j] = kk0 * (1.0f + (av[j] - 1.0f) * kac[j]);
;         const float t = rr[j] * k2[j]; bon += t * rkc[j]; c2 += t;
;         bu[j] = kn[j] * av[j]; c1 += bu[j] * rr[j];
;     }
;     ssq += dpp_f<0x121>(ssq); bon += dpp_f<0x121>(bon); c1 += dpp_f<0x121>(c1); c2 += dpp_f<0x121>(c2);
;     ssq += dpp_f<0x122>(ssq); bon += dpp_f<0x122>(bon); c1 += dpp_f<0x122>(c1); c2 += dpp_f<0x122>(c2);
;     ssq += dpp_f<0x124>(ssq); bon += dpp_f<0x124>(bon); c1 += dpp_f<0x124>(c1); c2 += dpp_f<0x124>(c2);
;     ssq += dpp_f<0x128>(ssq); bon += dpp_f<0x128>(bon); c1 += dpp_f<0x128>(c1); c2 += dpp_f<0x128>(c2);
;     const float inv = __builtin_amdgcn_rsqf(fmaxf(ssq, 1e-24f));
;     f32x4 o_al, o_be, o_wr;
; #pragma unroll
;     for (int j = 0; j < 4; ++j) { o_al[j] = -(kn[j] * inv); o_be[j] = bu[j] * inv; o_wr[j] = dec[j] * rr[j]; }
;     LAS f32x4* s4 = (LAS f32x4*)slot;
;     s4[cq] = (f32x4){dec[0], dec[1], dec[2], dec[3]}; s4[16 + cq] = (f32x4){k2[0], k2[1], k2[2], k2[3]}; s4[32 + cq] = o_al; s4[48 + cq] = o_be; s4[64 + cq] = o_wr;
;     s4[80 + cq] = (f32x4){vv[0], vv[1], vv[2], vv[3]};
;     if (cq == 0) *(LAS f32x2*)(slot + 384) = (f32x2){c1 * inv, c2};
.LBB0_1109:
	s_waitcnt vmcnt(8)
	v_lshlrev_b32_e32 v108, 16, v46
	v_and_b32_e32 v109, 0xffff0000, v46
	v_lshlrev_b32_e32 v110, 16, v38
	v_and_b32_e32 v111, 0xffff0000, v38
	v_pk_add_f32 v[110:111], v[110:111], v[108:109] neg_lo:[0,1] neg_hi:[0,1]
	v_lshlrev_b32_e32 v140, 16, v39
	v_pk_fma_f32 v[144:145], v[6:7], v[110:111], v[108:109]
	v_lshlrev_b32_e32 v110, 16, v47
	v_and_b32_e32 v111, 0xffff0000, v47
	v_and_b32_e32 v141, 0xffff0000, v39
	v_pk_add_f32 v[140:141], v[140:141], v[110:111] neg_lo:[0,1] neg_hi:[0,1]
	v_lshlrev_b32_e32 v118, 16, v40
	v_and_b32_e32 v119, 0xffff0000, v40
	v_pk_fma_f32 v[146:147], v[8:9], v[140:141], v[110:111]
	v_lshlrev_b32_e32 v140, 16, v34
	v_and_b32_e32 v141, 0xffff0000, v34
	s_waitcnt vmcnt(3)
	v_lshlrev_b32_e32 v142, 16, v48
	v_and_b32_e32 v143, 0xffff0000, v48
	v_pk_add_f32 v[140:141], v[140:141], v[118:119] neg_lo:[0,1] neg_hi:[0,1]
	v_pk_add_f32 v[148:149], v[142:143], -1.0 op_sel_hi:[1,0]
	v_pk_fma_f32 v[140:141], v[2:3], v[140:141], v[118:119]
	v_pk_fma_f32 v[148:149], v[18:19], v[148:149], 1.0 op_sel_hi:[1,1,0]
	v_pk_mul_f32 v[154:155], v[14:15], v[140:141]
	v_pk_mul_f32 v[148:149], v[148:149], v[140:141]
	v_cvt_f32_f16_sdwa v141, v44 dst_sel:DWORD dst_unused:UNUSED_PAD src0_sel:WORD_1
	v_cvt_f32_f16_e32 v140, v44
	v_lshlrev_b32_e32 v114, 16, v36
	v_and_b32_e32 v115, 0xffff0000, v36
	v_lshlrev_b32_e32 v156, 16, v42
	v_and_b32_e32 v157, 0xffff0000, v42
	v_pk_add_f32 v[152:153], v[140:141], 1.0 op_sel_hi:[1,0] neg_lo:[1,0] neg_hi:[1,0]
	v_pk_add_f32 v[140:141], v[156:157], v[114:115] neg_lo:[0,1] neg_hi:[0,1]
	v_lshlrev_b32_e32 v116, 16, v41
	v_pk_fma_f32 v[164:165], v[10:11], v[140:141], v[114:115]
	v_and_b32_e32 v117, 0xffff0000, v41
	v_pk_mul_f32 v[140:141], v[164:165], v[148:149]
	v_pk_mul_f32 v[150:151], v[154:155], v[154:155]
	v_fma_f32 v33, v22, v140, 0
	v_add_f32_e32 v28, 0, v140
	v_fmac_f32_e32 v33, v23, v141
	v_add_f32_e32 v168, v141, v28
	v_lshlrev_b32_e32 v140, 16, v35
	v_and_b32_e32 v141, 0xffff0000, v35
	v_pk_add_f32 v[140:141], v[140:141], v[116:117] neg_lo:[0,1] neg_hi:[0,1]
	v_add_f32_e32 v28, v150, v151
	v_pk_fma_f32 v[140:141], v[4:5], v[140:141], v[116:117]
	v_pk_mul_f32 v[142:143], v[154:155], v[142:143]
	v_pk_mul_f32 v[158:159], v[16:17], v[140:141]
	v_pk_mul_f32 v[156:157], v[164:165], v[142:143]
	v_pk_mul_f32 v[160:161], v[158:159], v[158:159]
	v_add_f32_e32 v81, 0, v156
	v_add_f32_e32 v28, v160, v28
	v_add_f32_e32 v28, v161, v28
	v_add_f32_e32 v81, v157, v81
	v_lshlrev_b32_e32 v156, 16, v49
	v_add_f32_dpp v28, v28, v28 row_ror:1 row_mask:0xf bank_mask:0xf bound_ctrl:1
	v_and_b32_e32 v157, 0xffff0000, v49
	v_lshlrev_b32_e32 v112, 16, v37
	v_add_f32_dpp v28, v28, v28 row_ror:2 row_mask:0xf bank_mask:0xf bound_ctrl:1
	v_and_b32_e32 v113, 0xffff0000, v37
	v_pk_add_f32 v[162:163], v[156:157], -1.0 op_sel_hi:[1,0]
	v_add_f32_dpp v28, v28, v28 row_ror:4 row_mask:0xf bank_mask:0xf bound_ctrl:1
	v_pk_fma_f32 v[150:151], v[20:21], v[162:163], 1.0 op_sel_hi:[1,1,0]
	v_pk_mul_f32 v[164:165], v[164:165], 1.0 op_sel_hi:[1,0]
	v_add_f32_dpp v28, v28, v28 row_ror:8 row_mask:0xf bank_mask:0xf bound_ctrl:1
	v_max_f32_e32 v28, 0x179abe15, v28
	v_rsq_f32_e32 v28, v28
	v_pk_mul_f32 v[150:151], v[150:151], v[140:141]
	v_pk_mul_f32 v[140:141], v[158:159], v[156:157]
	v_pk_mul_f32 v[160:161], v[142:143], v[28:29] op_sel_hi:[1,0]
	v_lshlrev_b32_e32 v142, 16, v43
	v_and_b32_e32 v143, 0xffff0000, v43
	v_pk_add_f32 v[142:143], v[142:143], v[112:113] neg_lo:[0,1] neg_hi:[0,1]
	v_pk_mul_f32 v[162:163], v[140:141], v[28:29] op_sel_hi:[1,0]
	v_pk_fma_f32 v[166:167], v[12:13], v[142:143], v[112:113]
	v_pk_mul_f32 v[156:157], v[154:155], v[28:29] op_sel_hi:[1,0] neg_lo:[0,1] neg_hi:[0,1]
	v_pk_mul_f32 v[142:143], v[166:167], v[150:151]
	v_pk_mul_f32 v[140:141], v[166:167], v[140:141]
	v_fmac_f32_e32 v33, v24, v142
	v_add_f32_e32 v142, v142, v168
	v_add_f32_e32 v81, v140, v81
	v_cvt_f32_f16_sdwa v155, v45 dst_sel:DWORD dst_unused:UNUSED_PAD src0_sel:WORD_1
	v_cvt_f32_f16_e32 v154, v45
	v_fmac_f32_e32 v33, v25, v143
	v_add_f32_e32 v140, v143, v142
	v_add_f32_e32 v81, v141, v81
	v_add_f32_dpp v33, v33, v33 row_ror:1 row_mask:0xf bank_mask:0xf bound_ctrl:1
	v_add_f32_dpp v140, v140, v140 row_ror:1 row_mask:0xf bank_mask:0xf bound_ctrl:1
	v_add_f32_dpp v81, v81, v81 row_ror:1 row_mask:0xf bank_mask:0xf bound_ctrl:1
	v_add_f32_dpp v33, v33, v33 row_ror:2 row_mask:0xf bank_mask:0xf bound_ctrl:1
	v_add_f32_dpp v140, v140, v140 row_ror:2 row_mask:0xf bank_mask:0xf bound_ctrl:1
	v_add_f32_dpp v81, v81, v81 row_ror:2 row_mask:0xf bank_mask:0xf bound_ctrl:1
	v_add_f32_dpp v33, v33, v33 row_ror:4 row_mask:0xf bank_mask:0xf bound_ctrl:1
	v_add_f32_dpp v140, v140, v140 row_ror:4 row_mask:0xf bank_mask:0xf bound_ctrl:1
	v_add_f32_dpp v141, v81, v81 row_ror:4 row_mask:0xf bank_mask:0xf bound_ctrl:1
	v_mov_b32_e32 v142, 0
	v_mov_b32_e32 v143, 0
	v_mov_b32_e32 v81, 0
	v_pk_add_f32 v[154:155], v[154:155], 1.0 op_sel_hi:[1,0] neg_lo:[1,0] neg_hi:[1,0]
	v_mov_b32_dpp v142, v141 row_ror:8 row_mask:0xf bank_mask:0xf
	v_mov_b32_dpp v143, v140 row_ror:8 row_mask:0xf bank_mask:0xf
	v_mov_b32_dpp v81, v33 row_ror:8 row_mask:0xf bank_mask:0xf
	v_pk_mul_f32 v[158:159], v[158:159], v[28:29] op_sel_hi:[1,0] neg_lo:[0,1] neg_hi:[0,1]
	v_pk_mul_f32 v[166:167], v[166:167], 1.0 op_sel_hi:[1,0]
	ds_write_b128 v127, v[152:155] offset:50176
	s_nop 7
	s_nop 7
	ds_write_b128 v127, v[148:151] offset:50432
	s_nop 7
	s_nop 7
	ds_write_b128 v127, v[156:159] offset:50688
	s_nop 7
	s_nop 7
	ds_write_b128 v127, v[160:163] offset:50944
	s_nop 7
	s_nop 7
	ds_write_b128 v127, v[164:167] offset:51200
	s_nop 7
	s_nop 7
	ds_write_b128 v127, v[144:147] offset:51456
	s_nop 7
	s_nop 7
	s_and_saveexec_b64 s[52:53], s[4:5]
	v_add_f32_e32 v141, v141, v142
	v_mul_f32_e32 v142, v141, v28
	v_add_f32_e32 v143, v140, v143
	ds_write_b64 v126, v[142:143] offset:51712
	s_or_b64 exec, exec, s[52:53]
	s_waitcnt vmcnt(17)
; #define LAS __attribute__((address_space(3)))
; __device__ __forceinline__ float scan_prepare(const ScanRegs& R, const u32x2 qr_, const u32x2 qk_, const u32x2 qv_, LAS float* slot, int cq, const f32x4 mur, const f32x4 muk, const f32x4 muv, const f32x4 kkc, const f32x4 kac, const f32x4 rkc) {
;     float pr[4], pk[4], pv[4], qr[4], qk[4], qv[4], av[4], om[4];
;     unpack4(R.pr, pr); unpack4(R.pk, pk); unpack4(R.pv, pv); unpack4(qr_, qr); unpack4(qk_, qk); unpack4(qv_, qv); unpack4(R.as, av);
;     om[0] = f16_to_f((unsigned short)(R.wl.x & 0xffffu)); om[1] = f16_to_f((unsigned short)(R.wl.x >> 16)); om[2] = f16_to_f((unsigned short)(R.wl.y & 0xffffu)); om[3] = f16_to_f((unsigned short)(R.wl.y >> 16));
;     float rr[4], vv[4], kn[4], k2[4], dec[4], bu[4];
;     float ssq = 0.f, bon = 0.f, c1 = 0.f, c2 = 0.f;
; #pragma unroll
;     for (int j = 0; j < 4; ++j) {
;         rr[j] = pr[j] + (qr[j] - pr[j]) * mur[j]; const float kk0 = pk[j] + (qk[j] - pk[j]) * muk[j]; vv[j] = pv[j] + (qv[j] - pv[j]) * muv[j];
;         dec[j] = 1.0f - om[j];
;         kn[j] = kk0 * kkc[j]; ssq += kn[j] * kn[j];
;         k2[j] = kk0 * (1.0f + (av[j] - 1.0f) * kac[j]);
;         const float t = rr[j] * k2[j]; bon += t * rkc[j]; c2 += t;
;         bu[j] = kn[j] * av[j]; c1 += bu[j] * rr[j];
;     }
;     ssq += dpp_f<0x121>(ssq); bon += dpp_f<0x121>(bon); c1 += dpp_f<0x121>(c1); c2 += dpp_f<0x121>(c2);
;     ssq += dpp_f<0x122>(ssq); bon += dpp_f<0x122>(bon); c1 += dpp_f<0x122>(c1); c2 += dpp_f<0x122>(c2);
;     ssq += dpp_f<0x124>(ssq); bon += dpp_f<0x124>(bon); c1 += dpp_f<0x124>(c1); c2 += dpp_f<0x124>(c2);
;     ssq += dpp_f<0x128>(ssq); bon += dpp_f<0x128>(bon); c1 += dpp_f<0x128>(c1); c2 += dpp_f<0x128>(c2);
;     const float inv = __builtin_amdgcn_rsqf(fmaxf(ssq, 1e-24f));
;     f32x4 o_al, o_be, o_wr;
; #pragma unroll
;     for (int j = 0; j < 4; ++j) { o_al[j] = -(kn[j] * inv); o_be[j] = bu[j] * inv; o_wr[j] = dec[j] * rr[j]; }
;     LAS f32x4* s4 = (LAS f32x4*)slot;
;     s4[cq] = (f32x4){dec[0], dec[1], dec[2], dec[3]}; s4[16 + cq] = (f32x4){k2[0], k2[1], k2[2], k2[3]}; s4[32 + cq] = o_al; s4[48 + cq] = o_be; s4[64 + cq] = o_wr;
;     s4[80 + cq] = (f32x4){vv[0], vv[1], vv[2], vv[3]};
;     if (cq == 0) *(LAS f32x2*)(slot + 384) = (f32x2){c1 * inv, c2};
;     return bon;
; }
	v_lshlrev_b32_e32 v140, 16, v50
	v_and_b32_e32 v141, 0xffff0000, v50
	s_waitcnt vmcnt(2)
	v_lshlrev_b32_e32 v142, 16, v58
	v_and_b32_e32 v143, 0xffff0000, v58
	v_pk_add_f32 v[118:119], v[118:119], v[140:141] neg_lo:[0,1] neg_hi:[0,1]
	v_lshlrev_b32_e32 v150, 16, v59
	v_pk_fma_f32 v[118:119], v[2:3], v[118:119], v[140:141]
	v_pk_add_f32 v[140:141], v[142:143], -1.0 op_sel_hi:[1,0]
	v_pk_mul_f32 v[146:147], v[14:15], v[118:119]
	v_pk_fma_f32 v[140:141], v[18:19], v[140:141], 1.0 op_sel_hi:[1,1,0]
	v_pk_mul_f32 v[152:153], v[146:147], v[142:143]
	v_pk_mul_f32 v[140:141], v[140:141], v[118:119]
	v_cvt_f32_f16_sdwa v119, v52 dst_sel:DWORD dst_unused:UNUSED_PAD src0_sel:WORD_1
	v_cvt_f32_f16_e32 v118, v52
	s_waitcnt vmcnt(6)
	v_lshlrev_b32_e32 v142, 16, v82
	v_and_b32_e32 v143, 0xffff0000, v82
	v_pk_add_f32 v[114:115], v[114:115], v[142:143] neg_lo:[0,1] neg_hi:[0,1]
	v_pk_add_f32 v[144:145], v[118:119], 1.0 op_sel_hi:[1,0] neg_lo:[1,0] neg_hi:[1,0]
	v_pk_fma_f32 v[118:119], v[10:11], v[114:115], v[142:143]
	v_pk_mul_f32 v[148:149], v[146:147], v[146:147]
	v_pk_mul_f32 v[114:115], v[118:119], v[140:141]
	v_pk_mul_f32 v[142:143], v[118:119], v[152:153]
	v_fma_f32 v156, v22, v114, 0
	v_add_f32_e32 v28, 0, v114
	v_add_f32_e32 v114, 0, v142
	v_fmac_f32_e32 v156, v23, v115
	v_add_f32_e32 v157, v115, v28
	v_add_f32_e32 v164, v143, v114
	v_lshlrev_b32_e32 v114, 16, v51
	v_and_b32_e32 v115, 0xffff0000, v51
	v_pk_add_f32 v[116:117], v[116:117], v[114:115] neg_lo:[0,1] neg_hi:[0,1]
	v_add_f32_e32 v28, v148, v149
	v_pk_fma_f32 v[114:115], v[4:5], v[116:117], v[114:115]
	v_and_b32_e32 v151, 0xffff0000, v59
	v_pk_mul_f32 v[116:117], v[16:17], v[114:115]
	v_pk_add_f32 v[154:155], v[150:151], -1.0 op_sel_hi:[1,0]
	v_pk_mul_f32 v[142:143], v[116:117], v[116:117]
	s_waitcnt vmcnt(5)
	v_lshlrev_b32_e32 v160, 16, v88
	v_add_f32_e32 v28, v142, v28
	v_add_f32_e32 v28, v143, v28
	v_pk_fma_f32 v[142:143], v[20:21], v[154:155], 1.0 op_sel_hi:[1,1,0]
	v_and_b32_e32 v161, 0xffff0000, v88
	v_add_f32_dpp v28, v28, v28 row_ror:1 row_mask:0xf bank_mask:0xf bound_ctrl:1
	v_pk_mul_f32 v[142:143], v[142:143], v[114:115]
	v_pk_mul_f32 v[114:115], v[116:117], v[150:151]
	v_add_f32_dpp v28, v28, v28 row_ror:2 row_mask:0xf bank_mask:0xf bound_ctrl:1
	v_lshlrev_b32_e32 v162, 16, v89
	v_and_b32_e32 v163, 0xffff0000, v89
	v_add_f32_dpp v28, v28, v28 row_ror:4 row_mask:0xf bank_mask:0xf bound_ctrl:1
	v_pk_add_f32 v[108:109], v[108:109], v[160:161] neg_lo:[0,1] neg_hi:[0,1]
	v_pk_add_f32 v[110:111], v[110:111], v[162:163] neg_lo:[0,1] neg_hi:[0,1]
	v_add_f32_dpp v28, v28, v28 row_ror:8 row_mask:0xf bank_mask:0xf bound_ctrl:1
	v_max_f32_e32 v28, 0x179abe15, v28
	v_rsq_f32_e32 v28, v28
	v_pk_fma_f32 v[110:111], v[8:9], v[110:111], v[162:163]
	v_pk_fma_f32 v[108:109], v[6:7], v[108:109], v[160:161]
	v_pk_mul_f32 v[150:151], v[116:117], v[28:29] op_sel_hi:[1,0] neg_lo:[0,1] neg_hi:[0,1]
	v_lshlrev_b32_e32 v116, 16, v83
	v_and_b32_e32 v117, 0xffff0000, v83
	v_pk_add_f32 v[112:113], v[112:113], v[116:117] neg_lo:[0,1] neg_hi:[0,1]
	v_pk_mul_f32 v[154:155], v[114:115], v[28:29] op_sel_hi:[1,0]
	v_pk_fma_f32 v[158:159], v[12:13], v[112:113], v[116:117]
	v_pk_mul_f32 v[148:149], v[146:147], v[28:29] op_sel_hi:[1,0] neg_lo:[0,1] neg_hi:[0,1]
	v_pk_mul_f32 v[112:113], v[158:159], v[142:143]
	v_pk_mul_f32 v[114:115], v[158:159], v[114:115]
	v_fmac_f32_e32 v156, v24, v112
	v_add_f32_e32 v112, v112, v157
	v_add_f32_e32 v114, v114, v164
	v_cvt_f32_f16_sdwa v147, v53 dst_sel:DWORD dst_unused:UNUSED_PAD src0_sel:WORD_1
	v_cvt_f32_f16_e32 v146, v53
	v_fmac_f32_e32 v156, v25, v113
	v_add_f32_e32 v112, v113, v112
	v_add_f32_e32 v113, v115, v114
	v_add_f32_dpp v114, v156, v156 row_ror:1 row_mask:0xf bank_mask:0xf bound_ctrl:1
	v_add_f32_dpp v112, v112, v112 row_ror:1 row_mask:0xf bank_mask:0xf bound_ctrl:1
	v_add_f32_dpp v113, v113, v113 row_ror:1 row_mask:0xf bank_mask:0xf bound_ctrl:1
	v_add_f32_dpp v114, v114, v114 row_ror:2 row_mask:0xf bank_mask:0xf bound_ctrl:1
	v_add_f32_dpp v116, v112, v112 row_ror:2 row_mask:0xf bank_mask:0xf bound_ctrl:1
	v_add_f32_dpp v113, v113, v113 row_ror:2 row_mask:0xf bank_mask:0xf bound_ctrl:1
	v_add_f32_dpp v112, v114, v114 row_ror:4 row_mask:0xf bank_mask:0xf bound_ctrl:1
	v_add_f32_dpp v114, v116, v116 row_ror:4 row_mask:0xf bank_mask:0xf bound_ctrl:1
	v_add_f32_dpp v115, v113, v113 row_ror:4 row_mask:0xf bank_mask:0xf bound_ctrl:1
	v_mov_b32_e32 v116, 0
	v_mov_b32_e32 v117, 0
	v_mov_b32_e32 v113, 0
	v_pk_add_f32 v[146:147], v[146:147], 1.0 op_sel_hi:[1,0] neg_lo:[1,0] neg_hi:[1,0]
	v_mov_b32_dpp v116, v115 row_ror:8 row_mask:0xf bank_mask:0xf
	v_mov_b32_dpp v117, v114 row_ror:8 row_mask:0xf bank_mask:0xf
	v_mov_b32_dpp v113, v112 row_ror:8 row_mask:0xf bank_mask:0xf
	v_pk_mul_f32 v[152:153], v[152:153], v[28:29] op_sel_hi:[1,0]
	v_pk_mul_f32 v[156:157], v[118:119], 1.0 op_sel_hi:[1,0]
	v_pk_mul_f32 v[158:159], v[158:159], 1.0 op_sel_hi:[1,0]
	ds_write_b128 v129, v[144:147] offset:50176
	s_nop 7
	s_nop 7
	ds_write_b128 v129, v[140:143] offset:50432
	s_nop 7
	s_nop 7
	ds_write_b128 v129, v[148:151] offset:50688
	s_nop 7
	s_nop 7
	ds_write_b128 v129, v[152:155] offset:50944
	s_nop 7
	s_nop 7
	ds_write_b128 v129, v[156:159] offset:51200
	s_nop 7
	s_nop 7
	ds_write_b128 v129, v[108:111] offset:51456
	s_nop 7
	s_nop 7
	s_and_saveexec_b64 s[52:53], s[4:5]
	s_cbranch_execz .LBB0_1121
	v_add_f32_e32 v108, v115, v116
	v_mul_f32_e32 v108, v108, v28
	v_add_f32_e32 v109, v114, v117
	ds_write_b64 v128, v[108:109] offset:51712
	s_or_b64 exec, exec, s[52:53]
	s_and_saveexec_b64 s[52:53], s[44:45]
	s_cbranch_execnz .LBB0_1122

; #define LAS __attribute__((address_space(3)))
; __device__ __forceinline__ float f16_to_f(unsigned short h) { return (float)__builtin_bit_cast(_Float16, h); }
; __device__ __forceinline__ float scan_prepare(const ScanRegs& R, const u32x2 qr_, const u32x2 qk_, const u32x2 qv_, LAS float* slot, int cq, const f32x4 mur, const f32x4 muk, const f32x4 muv, const f32x4 kkc, const f32x4 kac, const f32x4 rkc) {
;     float pr[4], pk[4], pv[4], qr[4], qk[4], qv[4], av[4], om[4];
;     unpack4(R.pr, pr); unpack4(R.pk, pk); unpack4(R.pv, pv); unpack4(qr_, qr); unpack4(qk_, qk); unpack4(qv_, qv); unpack4(R.as, av);
;     om[0] = f16_to_f((unsigned short)(R.wl.x & 0xffffu)); om[1] = f16_to_f((unsigned short)(R.wl.x >> 16)); om[2] = f16_to_f((unsigned short)(R.wl.y & 0xffffu)); om[3] = f16_to_f((unsigned short)(R.wl.y >> 16));
;     float rr[4], vv[4], kn[4], k2[4], dec[4], bu[4];
;     float ssq = 0.f, bon = 0.f, c1 = 0.f, c2 = 0.f;
; #pragma unroll
;     for (int j = 0; j < 4; ++j) {
;         rr[j] = pr[j] + (qr[j] - pr[j]) * mur[j]; const float kk0 = pk[j] + (qk[j] - pk[j]) * muk[j]; vv[j] = pv[j] + (qv[j] - pv[j]) * muv[j];
;         dec[j] = 1.0f - om[j];
;         kn[j] = kk0 * kkc[j]; ssq += kn[j] * kn[j];
;         k2[j] = kk0 * (1.0f + (av[j] - 1.0f) * kac[j]);
;         const float t = rr[j] * k2[j]; bon += t * rkc[j]; c2 += t;
;         bu[j] = kn[j] * av[j]; c1 += bu[j] * rr[j];
;     }
;     ssq += dpp_f<0x121>(ssq); bon += dpp_f<0x121>(bon); c1 += dpp_f<0x121>(c1); c2 += dpp_f<0x121>(c2);
;     ssq += dpp_f<0x122>(ssq); bon += dpp_f<0x122>(bon); c1 += dpp_f<0x122>(c1); c2 += dpp_f<0x122>(c2);
;     ssq += dpp_f<0x124>(ssq); bon += dpp_f<0x124>(bon); c1 += dpp_f<0x124>(c1); c2 += dpp_f<0x124>(c2);
;     ssq += dpp_f<0x128>(ssq); bon += dpp_f<0x128>(bon); c1 += dpp_f<0x128>(c1); c2 += dpp_f<0x128>(c2);
;     const float inv = __builtin_amdgcn_rsqf(fmaxf(ssq, 1e-24f));
;     f32x4 o_al, o_be, o_wr;
; #pragma unroll
;     for (int j = 0; j < 4; ++j) { o_al[j] = -(kn[j] * inv); o_be[j] = bu[j] * inv; o_wr[j] = dec[j] * rr[j]; }
;     LAS f32x4* s4 = (LAS f32x4*)slot;
;     s4[cq] = (f32x4){dec[0], dec[1], dec[2], dec[3]}; s4[16 + cq] = (f32x4){k2[0], k2[1], k2[2], k2[3]}; s4[32 + cq] = o_al; s4[48 + cq] = o_be; s4[64 + cq] = o_wr;
;     s4[80 + cq] = (f32x4){vv[0], vv[1], vv[2], vv[3]};
;     if (cq == 0) *(LAS f32x2*)(slot + 384) = (f32x2){c1 * inv, c2};
.LBB0_1115:
	v_add_u32_e32 v28, v120, v130
	s_waitcnt lgkmcnt(0)
	s_barrier
	ds_read_b128 v[108:111], v28
	v_lshl_add_u64 v[112:113], s[92:93], 0, v[100:101]
	v_add_co_u32_e32 v112, vcc, s68, v112
	s_cmpk_gt_u32 s14, 0xfd
	s_waitcnt lgkmcnt(0)
	v_add_f32_e32 v28, v108, v109
	v_add_f32_e32 v33, v110, v111
	v_add_f32_e32 v28, v28, v33
	v_bfe_u32 v33, v28, 16, 1
	v_add3_u32 v28, v28, v33, s67
	v_addc_co_u32_e32 v113, vcc, 0, v113, vcc
	global_store_short_d16_hi v[112:113], v28, off
	v_add_u32_e32 v28, v120, v131
	ds_read_b128 v[108:111], v28
	s_cselect_b64 s[52:53], -1, 0
	s_and_b64 vcc, exec, s[52:53]
	s_waitcnt lgkmcnt(0)
	v_add_f32_e32 v28, v108, v109
	v_add_f32_e32 v33, v110, v111
	v_add_f32_e32 v28, v28, v33
	v_bfe_u32 v33, v28, 16, 1
	v_add3_u32 v28, v28, v33, s67
	global_store_short_d16_hi v[112:113], v28, off offset:2048
	s_cbranch_vccnz .LBB0_1106
	v_lshlrev_b32_e32 v108, 16, v76
	v_and_b32_e32 v109, 0xffff0000, v76
	v_lshlrev_b32_e32 v110, 16, v62
	v_and_b32_e32 v111, 0xffff0000, v62
	v_pk_add_f32 v[110:111], v[110:111], v[108:109] neg_lo:[0,1] neg_hi:[0,1]
	v_lshlrev_b32_e32 v140, 16, v63
	v_pk_fma_f32 v[144:145], v[6:7], v[110:111], v[108:109]
	v_lshlrev_b32_e32 v110, 16, v77
	v_and_b32_e32 v111, 0xffff0000, v77
	v_and_b32_e32 v141, 0xffff0000, v63
	v_pk_add_f32 v[140:141], v[140:141], v[110:111] neg_lo:[0,1] neg_hi:[0,1]
	v_lshlrev_b32_e32 v118, 16, v64
	v_and_b32_e32 v119, 0xffff0000, v64
	v_pk_fma_f32 v[146:147], v[8:9], v[140:141], v[110:111]
	v_lshlrev_b32_e32 v140, 16, v54
	v_and_b32_e32 v141, 0xffff0000, v54
	s_waitcnt vmcnt(3)
	v_lshlrev_b32_e32 v142, 16, v86
	v_and_b32_e32 v143, 0xffff0000, v86
	v_pk_add_f32 v[140:141], v[140:141], v[118:119] neg_lo:[0,1] neg_hi:[0,1]
	v_pk_add_f32 v[148:149], v[142:143], -1.0 op_sel_hi:[1,0]
	v_pk_fma_f32 v[140:141], v[2:3], v[140:141], v[118:119]
	v_pk_fma_f32 v[148:149], v[18:19], v[148:149], 1.0 op_sel_hi:[1,1,0]
	v_pk_mul_f32 v[154:155], v[14:15], v[140:141]
	v_pk_mul_f32 v[148:149], v[140:141], v[148:149]
	v_cvt_f32_f16_sdwa v141, v72 dst_sel:DWORD dst_unused:UNUSED_PAD src0_sel:WORD_1
	v_cvt_f32_f16_e32 v140, v72
	v_lshlrev_b32_e32 v114, 16, v56
	v_and_b32_e32 v115, 0xffff0000, v56
	v_lshlrev_b32_e32 v156, 16, v68
	v_and_b32_e32 v157, 0xffff0000, v68
	v_pk_add_f32 v[152:153], v[140:141], 1.0 op_sel_hi:[1,0] neg_lo:[1,0] neg_hi:[1,0]
	v_pk_add_f32 v[140:141], v[156:157], v[114:115] neg_lo:[0,1] neg_hi:[0,1]
	v_lshlrev_b32_e32 v116, 16, v65
	v_pk_fma_f32 v[164:165], v[10:11], v[140:141], v[114:115]
	v_and_b32_e32 v117, 0xffff0000, v65
	v_pk_mul_f32 v[140:141], v[164:165], v[148:149]
	v_pk_mul_f32 v[150:151], v[154:155], v[154:155]
	v_fma_f32 v33, v22, v140, 0
	v_add_f32_e32 v28, 0, v140
	v_fmac_f32_e32 v33, v23, v141
	v_add_f32_e32 v168, v141, v28
	v_lshlrev_b32_e32 v140, 16, v55
	v_and_b32_e32 v141, 0xffff0000, v55
	v_pk_add_f32 v[140:141], v[140:141], v[116:117] neg_lo:[0,1] neg_hi:[0,1]
	v_add_f32_e32 v28, v150, v151
	v_pk_fma_f32 v[140:141], v[4:5], v[140:141], v[116:117]
	v_pk_mul_f32 v[142:143], v[154:155], v[142:143]
	v_pk_mul_f32 v[158:159], v[16:17], v[140:141]
	v_pk_mul_f32 v[156:157], v[164:165], v[142:143]
	v_pk_mul_f32 v[160:161], v[158:159], v[158:159]
	v_add_f32_e32 v81, 0, v156
	v_add_f32_e32 v28, v160, v28
	v_add_f32_e32 v28, v161, v28
	v_add_f32_e32 v81, v157, v81
	v_lshlrev_b32_e32 v156, 16, v87
	v_add_f32_dpp v28, v28, v28 row_ror:1 row_mask:0xf bank_mask:0xf bound_ctrl:1
	v_and_b32_e32 v157, 0xffff0000, v87
	v_lshlrev_b32_e32 v112, 16, v57
	v_add_f32_dpp v28, v28, v28 row_ror:2 row_mask:0xf bank_mask:0xf bound_ctrl:1
	v_and_b32_e32 v113, 0xffff0000, v57
	v_pk_add_f32 v[162:163], v[156:157], -1.0 op_sel_hi:[1,0]
	v_add_f32_dpp v28, v28, v28 row_ror:4 row_mask:0xf bank_mask:0xf bound_ctrl:1
	v_pk_fma_f32 v[150:151], v[20:21], v[162:163], 1.0 op_sel_hi:[1,1,0]
	v_pk_mul_f32 v[164:165], v[164:165], 1.0 op_sel_hi:[1,0]
	v_add_f32_dpp v28, v28, v28 row_ror:8 row_mask:0xf bank_mask:0xf bound_ctrl:1
	v_max_f32_e32 v28, 0x179abe15, v28
	v_rsq_f32_e32 v28, v28
	v_pk_mul_f32 v[150:151], v[140:141], v[150:151]
	v_pk_mul_f32 v[140:141], v[158:159], v[156:157]
	v_pk_mul_f32 v[160:161], v[142:143], v[28:29] op_sel_hi:[1,0]
	v_lshlrev_b32_e32 v142, 16, v69
	v_and_b32_e32 v143, 0xffff0000, v69
	v_pk_add_f32 v[142:143], v[142:143], v[112:113] neg_lo:[0,1] neg_hi:[0,1]
	v_pk_mul_f32 v[162:163], v[140:141], v[28:29] op_sel_hi:[1,0]
	v_pk_fma_f32 v[166:167], v[12:13], v[142:143], v[112:113]
	v_pk_mul_f32 v[156:157], v[154:155], v[28:29] op_sel_hi:[1,0] neg_lo:[0,1] neg_hi:[0,1]
	v_pk_mul_f32 v[142:143], v[166:167], v[150:151]
	v_pk_mul_f32 v[140:141], v[166:167], v[140:141]
	v_fmac_f32_e32 v33, v24, v142
	v_add_f32_e32 v142, v142, v168
	v_add_f32_e32 v81, v140, v81
	v_cvt_f32_f16_sdwa v155, v73 dst_sel:DWORD dst_unused:UNUSED_PAD src0_sel:WORD_1
	v_cvt_f32_f16_e32 v154, v73
	v_fmac_f32_e32 v33, v25, v143
	v_add_f32_e32 v140, v143, v142
	v_add_f32_e32 v81, v141, v81
	v_add_f32_dpp v33, v33, v33 row_ror:1 row_mask:0xf bank_mask:0xf bound_ctrl:1
	v_add_f32_dpp v140, v140, v140 row_ror:1 row_mask:0xf bank_mask:0xf bound_ctrl:1
	v_add_f32_dpp v81, v81, v81 row_ror:1 row_mask:0xf bank_mask:0xf bound_ctrl:1
	v_add_f32_dpp v33, v33, v33 row_ror:2 row_mask:0xf bank_mask:0xf bound_ctrl:1
	v_add_f32_dpp v140, v140, v140 row_ror:2 row_mask:0xf bank_mask:0xf bound_ctrl:1
	v_add_f32_dpp v81, v81, v81 row_ror:2 row_mask:0xf bank_mask:0xf bound_ctrl:1
	v_add_f32_dpp v33, v33, v33 row_ror:4 row_mask:0xf bank_mask:0xf bound_ctrl:1
	v_add_f32_dpp v140, v140, v140 row_ror:4 row_mask:0xf bank_mask:0xf bound_ctrl:1
	v_add_f32_dpp v141, v81, v81 row_ror:4 row_mask:0xf bank_mask:0xf bound_ctrl:1
	v_mov_b32_e32 v142, 0
	v_mov_b32_e32 v143, 0
	v_mov_b32_e32 v81, 0
	v_pk_add_f32 v[154:155], v[154:155], 1.0 op_sel_hi:[1,0] neg_lo:[1,0] neg_hi:[1,0]
	v_mov_b32_dpp v142, v141 row_ror:8 row_mask:0xf bank_mask:0xf
	v_mov_b32_dpp v143, v140 row_ror:8 row_mask:0xf bank_mask:0xf
	v_mov_b32_dpp v81, v33 row_ror:8 row_mask:0xf bank_mask:0xf
	v_pk_mul_f32 v[158:159], v[158:159], v[28:29] op_sel_hi:[1,0] neg_lo:[0,1] neg_hi:[0,1]
	v_pk_mul_f32 v[166:167], v[166:167], 1.0 op_sel_hi:[1,0]
	ds_write_b128 v127, v[152:155]
	s_nop 7
	s_nop 7
	ds_write_b128 v127, v[148:151] offset:256
	s_nop 7
	s_nop 7
	ds_write_b128 v127, v[156:159] offset:512
	s_nop 7
	s_nop 7
	ds_write_b128 v127, v[160:163] offset:768
	s_nop 7
	s_nop 7
	ds_write_b128 v127, v[164:167] offset:1024
	s_nop 7
	s_nop 7
	ds_write_b128 v127, v[144:147] offset:1280
	s_nop 7
	s_nop 7
	s_and_saveexec_b64 s[56:57], s[4:5]
	v_add_f32_e32 v141, v141, v142
	v_mul_f32_e32 v142, v141, v28
	v_add_f32_e32 v143, v140, v143
	ds_write_b64 v126, v[142:143] offset:1536
	s_or_b64 exec, exec, s[56:57]
	s_waitcnt vmcnt(4)
; #define LAS __attribute__((address_space(3)))
; __device__ __forceinline__ float scan_prepare(const ScanRegs& R, const u32x2 qr_, const u32x2 qk_, const u32x2 qv_, LAS float* slot, int cq, const f32x4 mur, const f32x4 muk, const f32x4 muv, const f32x4 kkc, const f32x4 kac, const f32x4 rkc) {
;     float pr[4], pk[4], pv[4], qr[4], qk[4], qv[4], av[4], om[4];
;     unpack4(R.pr, pr); unpack4(R.pk, pk); unpack4(R.pv, pv); unpack4(qr_, qr); unpack4(qk_, qk); unpack4(qv_, qv); unpack4(R.as, av);
;     om[0] = f16_to_f((unsigned short)(R.wl.x & 0xffffu)); om[1] = f16_to_f((unsigned short)(R.wl.x >> 16)); om[2] = f16_to_f((unsigned short)(R.wl.y & 0xffffu)); om[3] = f16_to_f((unsigned short)(R.wl.y >> 16));
;     float rr[4], vv[4], kn[4], k2[4], dec[4], bu[4];
;     float ssq = 0.f, bon = 0.f, c1 = 0.f, c2 = 0.f;
; #pragma unroll
;     for (int j = 0; j < 4; ++j) {
;         rr[j] = pr[j] + (qr[j] - pr[j]) * mur[j]; const float kk0 = pk[j] + (qk[j] - pk[j]) * muk[j]; vv[j] = pv[j] + (qv[j] - pv[j]) * muv[j];
;         dec[j] = 1.0f - om[j];
;         kn[j] = kk0 * kkc[j]; ssq += kn[j] * kn[j];
;         k2[j] = kk0 * (1.0f + (av[j] - 1.0f) * kac[j]);
;         const float t = rr[j] * k2[j]; bon += t * rkc[j]; c2 += t;
;         bu[j] = kn[j] * av[j]; c1 += bu[j] * rr[j];
;     }
;     ssq += dpp_f<0x121>(ssq); bon += dpp_f<0x121>(bon); c1 += dpp_f<0x121>(c1); c2 += dpp_f<0x121>(c2);
;     ssq += dpp_f<0x122>(ssq); bon += dpp_f<0x122>(bon); c1 += dpp_f<0x122>(c1); c2 += dpp_f<0x122>(c2);
;     ssq += dpp_f<0x124>(ssq); bon += dpp_f<0x124>(bon); c1 += dpp_f<0x124>(c1); c2 += dpp_f<0x124>(c2);
;     ssq += dpp_f<0x128>(ssq); bon += dpp_f<0x128>(bon); c1 += dpp_f<0x128>(c1); c2 += dpp_f<0x128>(c2);
;     const float inv = __builtin_amdgcn_rsqf(fmaxf(ssq, 1e-24f));
;     f32x4 o_al, o_be, o_wr;
; #pragma unroll
;     for (int j = 0; j < 4; ++j) { o_al[j] = -(kn[j] * inv); o_be[j] = bu[j] * inv; o_wr[j] = dec[j] * rr[j]; }
;     LAS f32x4* s4 = (LAS f32x4*)slot;
;     s4[cq] = (f32x4){dec[0], dec[1], dec[2], dec[3]}; s4[16 + cq] = (f32x4){k2[0], k2[1], k2[2], k2[3]}; s4[32 + cq] = o_al; s4[48 + cq] = o_be; s4[64 + cq] = o_wr;
;     s4[80 + cq] = (f32x4){vv[0], vv[1], vv[2], vv[3]};
;     if (cq == 0) *(LAS f32x2*)(slot + 384) = (f32x2){c1 * inv, c2};
;     return bon;
; }
	v_lshlrev_b32_e32 v140, 16, v96
	v_and_b32_e32 v141, 0xffff0000, v96
	s_waitcnt vmcnt(2)
	v_lshlrev_b32_e32 v142, 16, v102
	v_and_b32_e32 v143, 0xffff0000, v102
	v_pk_add_f32 v[118:119], v[118:119], v[140:141] neg_lo:[0,1] neg_hi:[0,1]
	v_lshlrev_b32_e32 v150, 16, v103
	v_pk_fma_f32 v[118:119], v[2:3], v[118:119], v[140:141]
	v_pk_add_f32 v[140:141], v[142:143], -1.0 op_sel_hi:[1,0]
	v_pk_mul_f32 v[146:147], v[14:15], v[118:119]
	v_pk_fma_f32 v[140:141], v[18:19], v[140:141], 1.0 op_sel_hi:[1,1,0]
	v_pk_mul_f32 v[152:153], v[146:147], v[142:143]
	v_pk_mul_f32 v[140:141], v[140:141], v[118:119]
	v_cvt_f32_f16_sdwa v119, v98 dst_sel:DWORD dst_unused:UNUSED_PAD src0_sel:WORD_1
	v_cvt_f32_f16_e32 v118, v98
	v_lshlrev_b32_e32 v142, 16, v84
	v_and_b32_e32 v143, 0xffff0000, v84
	v_pk_add_f32 v[114:115], v[114:115], v[142:143] neg_lo:[0,1] neg_hi:[0,1]
	v_pk_add_f32 v[144:145], v[118:119], 1.0 op_sel_hi:[1,0] neg_lo:[1,0] neg_hi:[1,0]
	v_pk_fma_f32 v[118:119], v[10:11], v[114:115], v[142:143]
	v_pk_mul_f32 v[148:149], v[146:147], v[146:147]
	v_pk_mul_f32 v[114:115], v[118:119], v[140:141]
	v_pk_mul_f32 v[142:143], v[118:119], v[152:153]
	v_fma_f32 v156, v22, v114, 0
	v_add_f32_e32 v28, 0, v114
	v_add_f32_e32 v114, 0, v142
	v_fmac_f32_e32 v156, v23, v115
	v_add_f32_e32 v157, v115, v28
	v_add_f32_e32 v164, v143, v114
	v_lshlrev_b32_e32 v114, 16, v97
	v_and_b32_e32 v115, 0xffff0000, v97
	v_pk_add_f32 v[116:117], v[116:117], v[114:115] neg_lo:[0,1] neg_hi:[0,1]
	v_add_f32_e32 v28, v148, v149
	v_pk_fma_f32 v[114:115], v[4:5], v[116:117], v[114:115]
	v_and_b32_e32 v151, 0xffff0000, v103
	v_pk_mul_f32 v[116:117], v[16:17], v[114:115]
	v_pk_add_f32 v[154:155], v[150:151], -1.0 op_sel_hi:[1,0]
	v_pk_mul_f32 v[142:143], v[116:117], v[116:117]
	v_lshlrev_b32_e32 v160, 16, v94
	v_add_f32_e32 v28, v142, v28
	v_add_f32_e32 v28, v143, v28
	v_pk_fma_f32 v[142:143], v[20:21], v[154:155], 1.0 op_sel_hi:[1,1,0]
	v_and_b32_e32 v161, 0xffff0000, v94
	v_add_f32_dpp v28, v28, v28 row_ror:1 row_mask:0xf bank_mask:0xf bound_ctrl:1
	v_pk_mul_f32 v[142:143], v[142:143], v[114:115]
	v_pk_mul_f32 v[114:115], v[116:117], v[150:151]
	v_add_f32_dpp v28, v28, v28 row_ror:2 row_mask:0xf bank_mask:0xf bound_ctrl:1
	v_lshlrev_b32_e32 v162, 16, v95
	v_and_b32_e32 v163, 0xffff0000, v95
	v_add_f32_dpp v28, v28, v28 row_ror:4 row_mask:0xf bank_mask:0xf bound_ctrl:1
	v_pk_add_f32 v[108:109], v[108:109], v[160:161] neg_lo:[0,1] neg_hi:[0,1]
	v_pk_add_f32 v[110:111], v[110:111], v[162:163] neg_lo:[0,1] neg_hi:[0,1]
	v_add_f32_dpp v28, v28, v28 row_ror:8 row_mask:0xf bank_mask:0xf bound_ctrl:1
	v_max_f32_e32 v28, 0x179abe15, v28
	v_rsq_f32_e32 v28, v28
	v_pk_fma_f32 v[110:111], v[8:9], v[110:111], v[162:163]
	v_pk_fma_f32 v[108:109], v[6:7], v[108:109], v[160:161]
	v_pk_mul_f32 v[150:151], v[116:117], v[28:29] op_sel_hi:[1,0] neg_lo:[0,1] neg_hi:[0,1]
	v_lshlrev_b32_e32 v116, 16, v85
	v_and_b32_e32 v117, 0xffff0000, v85
	v_pk_add_f32 v[112:113], v[112:113], v[116:117] neg_lo:[0,1] neg_hi:[0,1]
	v_pk_mul_f32 v[154:155], v[114:115], v[28:29] op_sel_hi:[1,0]
	v_pk_fma_f32 v[158:159], v[12:13], v[112:113], v[116:117]
	v_pk_mul_f32 v[148:149], v[146:147], v[28:29] op_sel_hi:[1,0] neg_lo:[0,1] neg_hi:[0,1]
	v_pk_mul_f32 v[112:113], v[158:159], v[142:143]
	v_pk_mul_f32 v[114:115], v[158:159], v[114:115]
	v_fmac_f32_e32 v156, v24, v112
	v_add_f32_e32 v112, v112, v157
	v_add_f32_e32 v114, v114, v164
	v_cvt_f32_f16_sdwa v147, v99 dst_sel:DWORD dst_unused:UNUSED_PAD src0_sel:WORD_1
	v_cvt_f32_f16_e32 v146, v99
	v_fmac_f32_e32 v156, v25, v113
	v_add_f32_e32 v112, v113, v112
	v_add_f32_e32 v113, v115, v114
	v_add_f32_dpp v114, v156, v156 row_ror:1 row_mask:0xf bank_mask:0xf bound_ctrl:1
	v_add_f32_dpp v112, v112, v112 row_ror:1 row_mask:0xf bank_mask:0xf bound_ctrl:1
	v_add_f32_dpp v113, v113, v113 row_ror:1 row_mask:0xf bank_mask:0xf bound_ctrl:1
	v_add_f32_dpp v114, v114, v114 row_ror:2 row_mask:0xf bank_mask:0xf bound_ctrl:1
	v_add_f32_dpp v116, v112, v112 row_ror:2 row_mask:0xf bank_mask:0xf bound_ctrl:1
	v_add_f32_dpp v113, v113, v113 row_ror:2 row_mask:0xf bank_mask:0xf bound_ctrl:1
	v_add_f32_dpp v112, v114, v114 row_ror:4 row_mask:0xf bank_mask:0xf bound_ctrl:1
	v_add_f32_dpp v114, v116, v116 row_ror:4 row_mask:0xf bank_mask:0xf bound_ctrl:1
	v_add_f32_dpp v115, v113, v113 row_ror:4 row_mask:0xf bank_mask:0xf bound_ctrl:1
	v_mov_b32_e32 v116, 0
	v_mov_b32_e32 v117, 0
	v_mov_b32_e32 v113, 0
	v_pk_add_f32 v[146:147], v[146:147], 1.0 op_sel_hi:[1,0] neg_lo:[1,0] neg_hi:[1,0]
	v_mov_b32_dpp v116, v115 row_ror:8 row_mask:0xf bank_mask:0xf
	v_mov_b32_dpp v117, v114 row_ror:8 row_mask:0xf bank_mask:0xf
	v_mov_b32_dpp v113, v112 row_ror:8 row_mask:0xf bank_mask:0xf
	v_pk_mul_f32 v[152:153], v[152:153], v[28:29] op_sel_hi:[1,0]
	v_pk_mul_f32 v[156:157], v[118:119], 1.0 op_sel_hi:[1,0]
	v_pk_mul_f32 v[158:159], v[158:159], 1.0 op_sel_hi:[1,0]
	ds_write_b128 v129, v[144:147]
	s_nop 7
	s_nop 7
	ds_write_b128 v129, v[140:143] offset:256
	s_nop 7
	s_nop 7
	ds_write_b128 v129, v[148:151] offset:512
	s_nop 7
	s_nop 7
	ds_write_b128 v129, v[152:155] offset:768
	s_nop 7
	s_nop 7
	ds_write_b128 v129, v[156:159] offset:1024
	s_nop 7
	s_nop 7
	ds_write_b128 v129, v[108:111] offset:1280
	s_nop 7
	s_nop 7
	s_and_saveexec_b64 s[56:57], s[4:5]
	s_cbranch_execz .LBB0_1123
	v_add_f32_e32 v108, v115, v116
	v_mul_f32_e32 v108, v108, v28
	v_add_f32_e32 v109, v114, v117
	ds_write_b64 v128, v[108:109] offset:1536
	s_or_b64 exec, exec, s[56:57]
	s_and_saveexec_b64 s[56:57], s[44:45]
	s_cbranch_execnz .LBB0_1124
